# HGRN chunk loops: removed compiler vmcnt(0) drains before the per-chunk barriers so next-chunk LDS-DMA overlaps the chunk compute
# baseline (speedup 1.0000x reference)
; DI u32 pack2bf(float lo, float hi) { f32x2 v = {lo, hi}; return __builtin_bit_cast(u32, __builtin_convertvector(v, bf2_t)); }
; DI u16 f2bf(float x) { return (u16)(pack2bf(x, 0.f) & 0xffffu); }
; DI float bf2f(u16 b) { return __uint_as_float(((u32)b) << 16); }
; DI float h2f(u16 b) { return (float)__builtin_bit_cast(_Float16, b); }
; template <int PASS>
; DI void hgrn_unit(const Params& p, int layer, int unit, char* smem) {
;     ...
; #pragma unroll
;     for (int j = 0; j < 32; ++j) {
;       float g = h2f(rG[j * 64 + lane]);
;       if (j < 16) tot0 += g; else tot1 += g;
;       if (j == 16) g16 = g;
;       if ((j >> 4) == half) gval[j & 15] = g;
;     }
; #pragma unroll
;     for (int jj = 0; jj < 16; ++jj) { if (PASS == 2) qraw[jj] = rQ[jj * 64 + lane]; vraw[jj] = rV[jj * 64 + lane]; }
;     asm volatile("s_waitcnt lgkmcnt(0)" ::: "memory");
;     __builtin_amdgcn_sched_barrier(0);
;     if (c + 1 < c_end) gl(c + 1);
;     __syncthreads();
;     const float bmid = tot0 + g16, blast = tot0 + tot1;
;     logD += blast;
;     float run = half ? tot0 : 0.f;
;     u32 klp[8], vtp[8];
;     if (PASS == 2) {
;       const float Emid = __expf(bmid), Elm = __expf(blast - bmid);
; #pragma unroll
;       for (int jj = 0; jj < 16; jj += 2) {
;         float kl2[2];
; #pragma unroll
;         for (int u = 0; u < 2; ++u) {
;           const int j = half * 16 + jj + u;
;           run += gval[jj + u];
;           float e1 = __expf(run - bmid), e2 = __expf(bmid - run);
;           float q = bf2f(qraw[jj + u]);
;           float k = 1.f - __expf(gval[jj + u]);
;           float qm = q * e1, km = k * e2;
;           kl2[u] = km * Elm;
;           sQm[j * HS + d] = f2bf(qm); sKm[j * HS + d] = f2bf(km); sQb[j * HS + d] = f2bf(qm * Emid);
;         }
;         klp[jj >> 1] = pack2bf(kl2[0], kl2[1]);
;       }
;     } else {
; #pragma unroll
;       for (int jj = 0; jj < 16; jj += 2) {
;         float kl2[2];
; #pragma unroll
;         for (int u = 0; u < 2; ++u) {
;           run += gval[jj + u];
;           kl2[u] = (1.f - __expf(gval[jj + u])) * __expf(blast - run);
;         }
;         klp[jj >> 1] = pack2bf(kl2[0], kl2[1]);
;       }
;     }
; #pragma unroll
;     for (int jj = 0; jj < 16; jj += 2)
;       vtp[jj >> 1] = (u32)vraw[jj] | ((u32)vraw[jj + 1] << 16);
.LBB0_578:
	s_waitcnt lgkmcnt(0)
	v_cvt_f32_f16_e32 v152, v152
	v_cvt_f32_f16_e32 v151, v151
	v_cvt_f32_f16_e32 v150, v150
	v_cvt_f32_f16_e32 v149, v149
	v_add_f32_e32 v153, 0, v152
	v_cvt_f32_f16_e32 v148, v148
	v_cndmask_b32_e32 v111, v111, v152, vcc
	v_add_f32_e32 v152, v153, v151
	v_cvt_f32_f16_e32 v147, v147
	v_cndmask_b32_e32 v110, v110, v151, vcc
	v_add_f32_e32 v151, v152, v150
	v_cvt_f32_f16_e32 v146, v146
	v_cndmask_b32_e32 v109, v109, v150, vcc
	v_add_f32_e32 v150, v151, v149
	v_cvt_f32_f16_e32 v145, v145
	v_cndmask_b32_e32 v108, v108, v149, vcc
	v_add_f32_e32 v149, v150, v148
	v_cvt_f32_f16_e32 v144, v144
	v_cndmask_b32_e32 v107, v107, v148, vcc
	v_add_f32_e32 v148, v149, v147
	v_cvt_f32_f16_e32 v143, v143
	v_cndmask_b32_e32 v106, v106, v147, vcc
	v_add_f32_e32 v147, v148, v146
	v_cvt_f32_f16_e32 v142, v142
	v_cndmask_b32_e32 v105, v105, v146, vcc
	v_add_f32_e32 v146, v147, v145
	v_cvt_f32_f16_e32 v141, v141
	v_cndmask_b32_e32 v104, v104, v145, vcc
	v_add_f32_e32 v145, v146, v144
	v_cvt_f32_f16_e32 v140, v140
	v_cndmask_b32_e32 v103, v103, v144, vcc
	v_add_f32_e32 v144, v145, v143
	v_cvt_f32_f16_e32 v139, v139
	v_cndmask_b32_e32 v102, v102, v143, vcc
	v_add_f32_e32 v143, v144, v142
	v_cvt_f32_f16_e32 v138, v138
	v_cndmask_b32_e32 v101, v101, v142, vcc
	v_add_f32_e32 v142, v143, v141
	v_cndmask_b32_e32 v100, v100, v141, vcc
	v_add_f32_e32 v141, v142, v140
	v_cndmask_b32_e32 v99, v99, v140, vcc
	v_add_f32_e32 v140, v141, v139
	v_cndmask_b32_e32 v98, v98, v139, vcc
	v_cvt_f32_f16_e32 v137, v137
	v_add_f32_e32 v139, v140, v138
	v_cndmask_b32_e32 v94, v94, v138, vcc
	v_cvt_f32_f16_e32 v138, v64
	v_cvt_f32_f16_e32 v136, v136
	v_cvt_f32_f16_e32 v135, v135
	v_cvt_f32_f16_e32 v134, v134
	v_add_f32_e32 v64, v139, v137
	v_cndmask_b32_e32 v75, v75, v137, vcc
	v_add_f32_e32 v137, 0, v138
	v_cvt_f32_f16_e32 v133, v133
	v_add_f32_e32 v137, v137, v136
	v_cvt_f32_f16_e32 v132, v132
	v_cndmask_b32_e64 v110, v110, v136, s[6:7]
	v_add_f32_e32 v136, v137, v135
	v_cvt_f32_f16_e32 v131, v131
	v_cndmask_b32_e64 v109, v109, v135, s[6:7]
	v_add_f32_e32 v135, v136, v134
	v_cvt_f32_f16_e32 v130, v130
	v_cndmask_b32_e64 v108, v108, v134, s[6:7]
	v_add_f32_e32 v134, v135, v133
	v_cvt_f32_f16_e32 v129, v129
	v_cndmask_b32_e64 v107, v107, v133, s[6:7]
	v_add_f32_e32 v133, v134, v132
	v_cvt_f32_f16_e32 v128, v128
	v_cndmask_b32_e64 v106, v106, v132, s[6:7]
	v_add_f32_e32 v132, v133, v131
	v_cvt_f32_f16_e32 v127, v127
	v_cndmask_b32_e64 v105, v105, v131, s[6:7]
	v_add_f32_e32 v131, v132, v130
	v_cvt_f32_f16_e32 v126, v126
	v_cndmask_b32_e64 v104, v104, v130, s[6:7]
	v_add_f32_e32 v130, v131, v129
	v_cvt_f32_f16_e32 v125, v125
	v_cndmask_b32_e64 v103, v103, v129, s[6:7]
	v_add_f32_e32 v129, v130, v128
	v_cvt_f32_f16_e32 v124, v124
	v_cndmask_b32_e64 v102, v102, v128, s[6:7]
	v_add_f32_e32 v128, v129, v127
	v_cndmask_b32_e64 v101, v101, v127, s[6:7]
	v_add_f32_e32 v127, v128, v126
	v_cndmask_b32_e64 v100, v100, v126, s[6:7]
	v_add_f32_e32 v126, v127, v125
	v_cvt_f32_f16_e32 v123, v123
	v_cndmask_b32_e64 v99, v99, v125, s[6:7]
	v_add_f32_e32 v125, v126, v124
	v_cvt_f32_f16_e32 v126, v74
	v_lshlrev_b32_e32 v115, 16, v115
	v_cndmask_b32_e64 v98, v98, v124, s[6:7]
	v_or_b32_sdwa v124, v115, v65 dst_sel:DWORD dst_unused:UNUSED_PAD src0_sel:DWORD src1_sel:WORD_0
	v_lshlrev_b32_e32 v65, 16, v116
	v_add_f32_e32 v74, v125, v123
	v_or_b32_sdwa v125, v65, v66 dst_sel:DWORD dst_unused:UNUSED_PAD src0_sel:DWORD src1_sel:WORD_0
	v_lshlrev_b32_e32 v65, 16, v117
	v_add_f32_e32 v74, v74, v126
	v_cndmask_b32_e64 v75, v75, v126, s[6:7]
	v_or_b32_sdwa v126, v65, v67 dst_sel:DWORD dst_unused:UNUSED_PAD src0_sel:DWORD src1_sel:WORD_0
	v_lshlrev_b32_e32 v65, 16, v118
	v_or_b32_sdwa v127, v65, v80 dst_sel:DWORD dst_unused:UNUSED_PAD src0_sel:DWORD src1_sel:WORD_0
	v_lshlrev_b32_e32 v65, 16, v119
	v_or_b32_sdwa v116, v65, v81 dst_sel:DWORD dst_unused:UNUSED_PAD src0_sel:DWORD src1_sel:WORD_0
	v_lshlrev_b32_e32 v65, 16, v120
	v_or_b32_sdwa v117, v65, v112 dst_sel:DWORD dst_unused:UNUSED_PAD src0_sel:DWORD src1_sel:WORD_0
	v_lshlrev_b32_e32 v65, 16, v121
	v_cndmask_b32_e64 v111, v111, v138, s[6:7]
	v_or_b32_sdwa v118, v65, v113 dst_sel:DWORD dst_unused:UNUSED_PAD src0_sel:DWORD src1_sel:WORD_0
	v_lshlrev_b32_e32 v65, 16, v122
	v_or_b32_sdwa v119, v65, v114 dst_sel:DWORD dst_unused:UNUSED_PAD src0_sel:DWORD src1_sel:WORD_0
	v_mul_f32_e32 v65, 0x3fb8aa3b, v111
	v_exp_f32_e32 v66, v65
	v_mul_f32_e32 v65, 0x3fb8aa3b, v110
	v_exp_f32_e32 v67, v65
	v_cndmask_b32_e64 v65, v64, 0, vcc
	v_add_f32_e32 v134, v65, v111
; DI u32 pack2bf(float lo, float hi) { f32x2 v = {lo, hi}; return __builtin_bit_cast(u32, __builtin_convertvector(v, bf2_t)); }
; template <int PASS>
; DI void hgrn_unit(const Params& p, int layer, int unit, char* smem) {
;     ...
;       for (int jj = 0; jj < 16; jj += 2) {
;         float kl2[2];
; #pragma unroll
;         for (int u = 0; u < 2; ++u) {
;           run += gval[jj + u];
;           kl2[u] = (1.f - __expf(gval[jj + u])) * __expf(blast - run);
;         }
;         klp[jj >> 1] = pack2bf(kl2[0], kl2[1]);
;       }
;     }
; #pragma unroll
;     for (int jj = 0; jj < 16; jj += 2)
;       vtp[jj >> 1] = (u32)vraw[jj] | ((u32)vraw[jj + 1] << 16);
;     {
;       u32x4 a = {klp[0], klp[1], klp[2], klp[3]}, b = {klp[4], klp[5], klp[6], klp[7]};
;       *(u32x4*)(sKlT + d * VS + half * 16) = a; *(u32x4*)(sKlT + d * VS + half * 16 + 8) = b;
;       u32x4 c0 = {vtp[0], vtp[1], vtp[2], vtp[3]}, c1 = {vtp[4], vtp[5], vtp[6], vtp[7]};
;       *(u32x4*)(sVt + d * VS + half * 16) = c0; *(u32x4*)(sVt + d * VS + half * 16 + 8) = c1;
;     }
;     if (half) sDec[d] = __expf(blast);
;     __syncthreads();
	v_mul_f32_e32 v65, 0x3fb8aa3b, v109
	v_exp_f32_e32 v80, v65
	v_mul_f32_e32 v65, 0x3fb8aa3b, v108
	v_add_f32_e32 v135, v134, v110
	v_exp_f32_e32 v81, v65
	v_add_f32_e32 v136, v135, v109
	v_mul_f32_e32 v65, 0x3fb8aa3b, v107
	v_add_f32_e32 v137, v136, v108
	v_exp_f32_e32 v112, v65
	v_mul_f32_e32 v65, 0x3fb8aa3b, v106
	v_exp_f32_e32 v113, v65
	v_add_f32_e32 v138, v137, v107
	v_mul_f32_e32 v65, 0x3fb8aa3b, v105
	v_pk_add_f32 v[114:115], v[80:81], 1.0 op_sel_hi:[1,0] neg_lo:[1,0] neg_hi:[1,0]
	v_add_f32_e32 v139, v138, v106
	v_exp_f32_e32 v80, v65
	v_mul_f32_e32 v65, 0x3fb8aa3b, v104
	v_add_f32_e32 v140, v139, v105
	v_exp_f32_e32 v81, v65
	v_add_f32_e32 v141, v140, v104
	v_mul_f32_e32 v65, 0x3fb8aa3b, v103
	v_pk_add_f32 v[120:121], v[112:113], 1.0 op_sel_hi:[1,0] neg_lo:[1,0] neg_hi:[1,0]
	v_exp_f32_e32 v112, v65
	v_mul_f32_e32 v65, 0x3fb8aa3b, v102
	v_add_f32_e32 v142, v141, v103
	v_exp_f32_e32 v113, v65
	v_add_f32_e32 v143, v142, v102
	v_mul_f32_e32 v65, 0x3fb8aa3b, v101
	v_cndmask_b32_e64 v94, v94, v123, s[6:7]
	v_pk_add_f32 v[122:123], v[80:81], 1.0 op_sel_hi:[1,0] neg_lo:[1,0] neg_hi:[1,0]
	v_add_f32_e32 v144, v143, v101
	v_exp_f32_e32 v80, v65
	v_mul_f32_e32 v65, 0x3fb8aa3b, v100
	v_add_f32_e32 v145, v144, v100
	v_exp_f32_e32 v81, v65
	v_mul_f32_e32 v65, 0x3fb8aa3b, v99
	v_add_f32_e32 v146, v145, v99
	v_pk_add_f32 v[128:129], v[112:113], 1.0 op_sel_hi:[1,0] neg_lo:[1,0] neg_hi:[1,0]
	v_exp_f32_e32 v112, v65
	v_mul_f32_e32 v65, 0x3fb8aa3b, v98
	v_add_f32_e32 v147, v146, v98
	v_exp_f32_e32 v113, v65
	v_add_f32_e32 v65, v147, v94
	v_pk_add_f32 v[130:131], v[80:81], 1.0 op_sel_hi:[1,0] neg_lo:[1,0] neg_hi:[1,0]
	v_pk_add_f32 v[80:81], v[64:65], v[74:75]
	v_pk_add_f32 v[132:133], v[112:113], 1.0 op_sel_hi:[1,0] neg_lo:[1,0] neg_hi:[1,0]
	v_sub_f32_e32 v64, v80, v134
	v_mul_f32_e32 v64, 0x3fb8aa3b, v64
	v_exp_f32_e32 v112, v64
	v_sub_f32_e32 v64, v80, v135
	v_mul_f32_e32 v64, 0x3fb8aa3b, v64
	v_exp_f32_e32 v113, v64
	v_sub_f32_e32 v64, v80, v136
	v_mul_f32_e32 v64, 0x3fb8aa3b, v64
	v_exp_f32_e32 v134, v64
	v_sub_f32_e32 v64, v80, v137
	v_mul_f32_e32 v64, 0x3fb8aa3b, v64
	v_exp_f32_e32 v135, v64
	v_pk_add_f32 v[66:67], v[66:67], 1.0 op_sel_hi:[1,0] neg_lo:[1,0] neg_hi:[1,0]
	v_sub_f32_e32 v74, v80, v138
	v_pk_mul_f32 v[66:67], v[66:67], v[112:113]
	v_mul_f32_e32 v74, 0x3fb8aa3b, v74
	v_cvt_pk_bf16_f32 v112, v66, v67
	v_pk_mul_f32 v[66:67], v[114:115], v[134:135]
	v_exp_f32_e32 v114, v74
	v_sub_f32_e32 v74, v80, v139
	v_mul_f32_e32 v74, 0x3fb8aa3b, v74
	v_exp_f32_e32 v115, v74
	v_sub_f32_e32 v74, v80, v140
	v_mul_f32_e32 v74, 0x3fb8aa3b, v74
	v_exp_f32_e32 v134, v74
	v_sub_f32_e32 v74, v80, v141
	v_mul_f32_e32 v74, 0x3fb8aa3b, v74
	v_exp_f32_e32 v135, v74
	v_sub_f32_e32 v74, v80, v142
	v_mul_f32_e32 v74, 0x3fb8aa3b, v74
	v_cvt_pk_bf16_f32 v113, v66, v67
	v_pk_mul_f32 v[66:67], v[120:121], v[114:115]
	v_exp_f32_e32 v120, v74
	v_sub_f32_e32 v74, v80, v143
	v_mul_f32_e32 v74, 0x3fb8aa3b, v74
	v_exp_f32_e32 v121, v74
	v_sub_f32_e32 v74, v80, v144
	v_mul_f32_e32 v74, 0x3fb8aa3b, v74
	v_cvt_pk_bf16_f32 v114, v66, v67
	v_pk_mul_f32 v[66:67], v[122:123], v[134:135]
	v_exp_f32_e32 v122, v74
	v_sub_f32_e32 v74, v80, v145
	v_mul_f32_e32 v74, 0x3fb8aa3b, v74
	v_exp_f32_e32 v123, v74
	v_cvt_pk_bf16_f32 v115, v66, v67
	v_pk_mul_f32 v[66:67], v[128:129], v[120:121]
	v_sub_f32_e32 v65, v80, v65
	v_cvt_pk_bf16_f32 v120, v66, v67
	v_pk_mul_f32 v[66:67], v[130:131], v[122:123]
	v_mul_f32_e32 v65, 0x3fb8aa3b, v65
	v_mul_f32_e32 v148, 0x3fb8aa3b, v94
	v_cvt_pk_bf16_f32 v121, v66, v67
	v_sub_f32_e32 v66, v80, v146
	v_sub_f32_e32 v67, v80, v147
	v_exp_f32_e32 v128, v65
	v_mul_f32_e32 v65, 0x3fb8aa3b, v75
	v_sub_f32_e32 v74, v80, v81
	v_exp_f32_e32 v64, v148
	v_mul_f32_e32 v66, 0x3fb8aa3b, v66
	v_mul_f32_e32 v67, 0x3fb8aa3b, v67
	v_exp_f32_e32 v65, v65
	v_mul_f32_e32 v74, 0x3fb8aa3b, v74
	v_exp_f32_e32 v66, v66
	v_exp_f32_e32 v67, v67
	v_exp_f32_e32 v129, v74
	v_pk_add_f32 v[64:65], v[64:65], 1.0 op_sel_hi:[1,0] neg_lo:[1,0] neg_hi:[1,0]
	s_nop 0
	v_pk_mul_f32 v[66:67], v[132:133], v[66:67]
	v_pk_mul_f32 v[64:65], v[64:65], v[128:129]
	s_barrier
	v_cvt_pk_bf16_f32 v122, v66, v67
	v_cvt_pk_bf16_f32 v123, v64, v65
	ds_write_b128 v83, v[112:115] offset:26112
	ds_write_b128 v83, v[120:123] offset:26128
	ds_write_b128 v83, v[124:127] offset:36352
	ds_write_b128 v83, v[116:119] offset:36368
	s_and_saveexec_b64 s[14:15], s[0:1]
	s_cbranch_execz .LBB0_575
	v_mul_f32_e32 v64, 0x3fb8aa3b, v80
	v_exp_f32_e32 v64, v64
	ds_write_b32 v82, v64 offset:46592
	s_branch .LBB0_575

; DI u16 f2bf(float x) { return (u16)(pack2bf(x, 0.f) & 0xffffu); }
; DI float bf2f(u16 b) { return __uint_as_float(((u32)b) << 16); }
; DI float h2f(u16 b) { return (float)__builtin_bit_cast(_Float16, b); }
; template <int PASS>
; DI void hgrn_unit(const Params& p, int layer, int unit, char* smem) {
;     ...
; #pragma unroll
;     for (int j = 0; j < 32; ++j) {
;       float g = h2f(rG[j * 64 + lane]);
;       if (j < 16) tot0 += g; else tot1 += g;
;       if (j == 16) g16 = g;
;       if ((j >> 4) == half) gval[j & 15] = g;
;     }
; #pragma unroll
;     for (int jj = 0; jj < 16; ++jj) { if (PASS == 2) qraw[jj] = rQ[jj * 64 + lane]; vraw[jj] = rV[jj * 64 + lane]; }
;     asm volatile("s_waitcnt lgkmcnt(0)" ::: "memory");
;     __builtin_amdgcn_sched_barrier(0);
;     if (c + 1 < c_end) gl(c + 1);
;     __syncthreads();
;     const float bmid = tot0 + g16, blast = tot0 + tot1;
;     logD += blast;
;     float run = half ? tot0 : 0.f;
;     u32 klp[8], vtp[8];
;     if (PASS == 2) {
;       const float Emid = __expf(bmid), Elm = __expf(blast - bmid);
; #pragma unroll
;       for (int jj = 0; jj < 16; jj += 2) {
;         float kl2[2];
; #pragma unroll
;         for (int u = 0; u < 2; ++u) {
;           const int j = half * 16 + jj + u;
;           run += gval[jj + u];
;           float e1 = __expf(run - bmid), e2 = __expf(bmid - run);
;           float q = bf2f(qraw[jj + u]);
;           float k = 1.f - __expf(gval[jj + u]);
;           float qm = q * e1, km = k * e2;
;           kl2[u] = km * Elm;
;           sQm[j * HS + d] = f2bf(qm); sKm[j * HS + d] = f2bf(km); sQb[j * HS + d] = f2bf(qm * Emid);
.LBB0_606:
	s_waitcnt lgkmcnt(0)
	v_cvt_f32_f16_e32 v168, v168
	v_cvt_f32_f16_e32 v167, v167
	v_cvt_f32_f16_e32 v166, v166
	v_cvt_f32_f16_e32 v165, v165
	v_add_f32_e32 v169, 0, v168
	v_cvt_f32_f16_e32 v164, v164
	v_cndmask_b32_e64 v121, v121, v168, s[42:43]
	v_add_f32_e32 v168, v169, v167
	v_cvt_f32_f16_e32 v163, v163
	v_cndmask_b32_e64 v122, v122, v167, s[42:43]
	v_add_f32_e32 v167, v168, v166
	v_cvt_f32_f16_e32 v162, v162
	v_cndmask_b32_e64 v123, v123, v166, s[42:43]
	v_add_f32_e32 v166, v167, v165
	v_cvt_f32_f16_e32 v161, v161
	v_cndmask_b32_e64 v124, v124, v165, s[42:43]
	v_add_f32_e32 v165, v166, v164
	v_cvt_f32_f16_e32 v160, v160
	v_cndmask_b32_e64 v125, v125, v164, s[42:43]
	v_add_f32_e32 v164, v165, v163
	v_cvt_f32_f16_e32 v159, v159
	v_cndmask_b32_e64 v126, v126, v163, s[42:43]
	v_add_f32_e32 v163, v164, v162
	v_cvt_f32_f16_e32 v158, v158
	v_cndmask_b32_e64 v127, v127, v162, s[42:43]
	v_add_f32_e32 v162, v163, v161
	v_cvt_f32_f16_e32 v157, v157
	v_cndmask_b32_e64 v128, v128, v161, s[42:43]
	v_add_f32_e32 v161, v162, v160
	v_cvt_f32_f16_e32 v156, v156
	v_cndmask_b32_e64 v129, v129, v160, s[42:43]
	v_add_f32_e32 v160, v161, v159
	v_cvt_f32_f16_e32 v155, v155
	v_cndmask_b32_e64 v130, v130, v159, s[42:43]
	v_add_f32_e32 v159, v160, v158
	v_cndmask_b32_e64 v131, v131, v158, s[42:43]
	v_add_f32_e32 v158, v159, v157
	v_cndmask_b32_e64 v132, v132, v157, s[42:43]
	v_add_f32_e32 v157, v158, v156
	v_cndmask_b32_e64 v133, v133, v156, s[42:43]
	v_add_f32_e32 v156, v157, v155
	v_cndmask_b32_e64 v136, v136, v155, s[42:43]
	v_cvt_f32_f16_e32 v155, v153
	v_cvt_f32_f16_e32 v153, v152
	v_cvt_f32_f16_e32 v151, v151
	v_cvt_f32_f16_e32 v150, v150
	v_cvt_f32_f16_e32 v149, v149
	v_add_f32_e32 v152, 0, v153
	v_cvt_f32_f16_e32 v148, v148
	v_add_f32_e32 v152, v152, v151
	v_cvt_f32_f16_e32 v147, v147
	v_cndmask_b32_e64 v122, v122, v151, s[6:7]
	v_add_f32_e32 v151, v152, v150
	v_cvt_f32_f16_e32 v146, v146
	v_cndmask_b32_e64 v123, v123, v150, s[6:7]
	v_add_f32_e32 v150, v151, v149
	v_cvt_f32_f16_e32 v145, v145
	v_cndmask_b32_e64 v124, v124, v149, s[6:7]
	v_add_f32_e32 v149, v150, v148
	v_cvt_f32_f16_e32 v144, v144
	v_cndmask_b32_e64 v125, v125, v148, s[6:7]
	v_add_f32_e32 v148, v149, v147
	v_cvt_f32_f16_e32 v94, v94
	v_cndmask_b32_e64 v126, v126, v147, s[6:7]
	v_add_f32_e32 v147, v148, v146
	v_cvt_f32_f16_e32 v93, v93
	v_cndmask_b32_e64 v127, v127, v146, s[6:7]
	v_add_f32_e32 v146, v147, v145
	v_cvt_f32_f16_e32 v92, v92
	v_cndmask_b32_e64 v128, v128, v145, s[6:7]
	v_add_f32_e32 v145, v146, v144
	v_cvt_f32_f16_e32 v71, v71
	v_cndmask_b32_e64 v129, v129, v144, s[6:7]
	v_add_f32_e32 v144, v145, v94
	v_cvt_f32_f16_e32 v66, v66
	v_cvt_f32_f16_e32 v154, v154
	v_cndmask_b32_e64 v130, v130, v94, s[6:7]
	v_add_f32_e32 v94, v144, v93
	v_cvt_f32_f16_e32 v65, v65
	v_cndmask_b32_e64 v131, v131, v93, s[6:7]
	v_add_f32_e32 v93, v94, v92
	v_cvt_f32_f16_e32 v64, v64
	v_cndmask_b32_e64 v132, v132, v92, s[6:7]
	v_add_f32_e32 v92, v93, v71
	v_cndmask_b32_e64 v133, v133, v71, s[6:7]
	v_add_f32_e32 v71, v92, v66
	v_add_f32_e32 v156, v156, v154
	v_cndmask_b32_e64 v134, v134, v155, s[42:43]
	v_cndmask_b32_e64 v136, v136, v66, s[6:7]
	v_add_f32_e32 v66, v71, v65
	v_cndmask_b32_e64 v135, v135, v154, s[42:43]
	v_add_f32_e32 v154, v156, v155
	v_add_f32_e32 v152, v66, v64
	v_cndmask_b32_e64 v134, v134, v64, s[6:7]
	v_lshlrev_b32_e32 v64, 16, v76
	v_cndmask_b32_e64 v121, v121, v153, s[6:7]
	v_or_b32_sdwa v64, v64, v67 dst_sel:DWORD dst_unused:UNUSED_PAD src0_sel:DWORD src1_sel:WORD_0
	v_lshlrev_b32_e32 v67, 16, v91
	v_cndmask_b32_e64 v91, v154, 0, s[42:43]
	v_cndmask_b32_e64 v135, v135, v65, s[6:7]
	v_lshlrev_b32_e32 v65, 16, v77
	v_pk_add_f32 v[76:77], v[154:155], v[152:153] op_sel_hi:[0,1]
	v_add_f32_e32 v91, v91, v121
	v_sub_f32_e32 v92, v91, v77
	v_mul_f32_e32 v92, 0x3fb8aa3b, v92
	v_exp_f32_e32 v93, v92
	v_or_b32_sdwa v65, v65, v68 dst_sel:DWORD dst_unused:UNUSED_PAD src0_sel:DWORD src1_sel:WORD_0
	v_lshlrev_b32_e32 v68, 16, v140
	v_lshlrev_b32_e32 v66, 16, v78
	v_or_b32_sdwa v68, v68, v95 dst_sel:DWORD dst_unused:UNUSED_PAD src0_sel:DWORD src1_sel:WORD_0
	v_mul_f32_e32 v78, 0x3fb8aa3b, v77
	v_lshlrev_b32_e32 v95, 16, v90
	v_exp_f32_e32 v94, v78
	v_mul_f32_e32 v93, v93, v95
	v_cvt_pk_bf16_f32 v95, v93, s0
	s_nop 0
	s_barrier
; DI u32 pack2bf(float lo, float hi) { f32x2 v = {lo, hi}; return __builtin_bit_cast(u32, __builtin_convertvector(v, bf2_t)); }
; DI u16 f2bf(float x) { return (u16)(pack2bf(x, 0.f) & 0xffffu); }
; DI float bf2f(u16 b) { return __uint_as_float(((u32)b) << 16); }
; template <int PASS>
; DI void hgrn_unit(const Params& p, int layer, int unit, char* smem) {
;     ...
;       for (int jj = 0; jj < 16; jj += 2) {
;         float kl2[2];
; #pragma unroll
;         for (int u = 0; u < 2; ++u) {
;           const int j = half * 16 + jj + u;
;           run += gval[jj + u];
;           float e1 = __expf(run - bmid), e2 = __expf(bmid - run);
;           float q = bf2f(qraw[jj + u]);
;           float k = 1.f - __expf(gval[jj + u]);
;           float qm = q * e1, km = k * e2;
;           kl2[u] = km * Elm;
;           sQm[j * HS + d] = f2bf(qm); sKm[j * HS + d] = f2bf(km); sQb[j * HS + d] = f2bf(qm * Emid);
;         }
;         klp[jj >> 1] = pack2bf(kl2[0], kl2[1]);
;       }
	ds_write_b16 v117, v95
	v_add_f32_e32 v95, v91, v122
	v_sub_f32_e32 v92, v77, v91
	v_sub_f32_e32 v91, v95, v77
	v_or_b32_sdwa v66, v66, v69 dst_sel:DWORD dst_unused:UNUSED_PAD src0_sel:DWORD src1_sel:WORD_0
	v_lshlrev_b32_e32 v69, 16, v141
	v_mul_f32_e32 v93, v94, v93
	v_mul_f32_e32 v91, 0x3fb8aa3b, v91
	v_or_b32_sdwa v69, v69, v137 dst_sel:DWORD dst_unused:UNUSED_PAD src0_sel:DWORD src1_sel:WORD_0
	v_cvt_pk_bf16_f32 v93, v93, s0
	v_exp_f32_e32 v137, v91
	v_sub_f32_e32 v91, v77, v95
	v_mul_f32_e32 v90, 0x3fb8aa3b, v121
	ds_write_b16 v117, v93 offset:17408
	v_mul_f32_e32 v93, 0x3fb8aa3b, v91
	v_mul_f32_e32 v91, 0x3fb8aa3b, v122
	v_mul_f32_e32 v92, 0x3fb8aa3b, v92
	v_exp_f32_e32 v90, v90
	v_exp_f32_e32 v91, v91
	v_sub_f32_e32 v78, v76, v77
	v_exp_f32_e32 v92, v92
	v_exp_f32_e32 v93, v93
	v_mul_f32_e32 v78, 0x3fb8aa3b, v78
	v_exp_f32_e32 v78, v78
	v_pk_add_f32 v[90:91], v[90:91], 1.0 op_sel_hi:[1,0] neg_lo:[1,0] neg_hi:[1,0]
	v_lshlrev_b32_e32 v72, 16, v72
	v_pk_mul_f32 v[90:91], v[90:91], v[92:93]
	v_mul_f32_e32 v72, v137, v72
	v_cvt_pk_bf16_f32 v92, v90, s0
	ds_write_b16 v117, v92 offset:8704
	v_pk_mul_f32 v[92:93], v[90:91], v[78:79] op_sel_hi:[1,0]
	v_cvt_pk_bf16_f32 v90, v72, s0
	ds_write_b16 v117, v90 offset:272
	v_cvt_pk_bf16_f32 v90, v91, s0
	v_add_f32_e32 v91, v95, v123
	ds_write_b16 v117, v90 offset:8976
	v_mul_f32_e32 v72, v94, v72
	v_sub_f32_e32 v90, v91, v77
	v_cvt_pk_bf16_f32 v72, v72, s0
	v_mul_f32_e32 v90, 0x3fb8aa3b, v90
	ds_write_b16 v117, v72 offset:17680
	v_cvt_pk_bf16_f32 v72, v92, v93
	v_exp_f32_e32 v93, v90
	v_lshlrev_b32_e32 v89, 16, v89
	v_sub_f32_e32 v90, v77, v91
	v_mul_f32_e32 v92, 0x3fb8aa3b, v123
	v_mul_f32_e32 v89, v93, v89
	v_cvt_pk_bf16_f32 v93, v89, s0
	v_mul_f32_e32 v89, v94, v89
	v_cvt_pk_bf16_f32 v89, v89, s0
	ds_write_b16 v117, v89 offset:17952
	v_add_f32_e32 v89, v91, v124
	v_sub_f32_e32 v91, v89, v77
	v_mul_f32_e32 v91, 0x3fb8aa3b, v91
	ds_write_b16 v117, v93 offset:544
	v_exp_f32_e32 v95, v91
	v_sub_f32_e32 v91, v77, v89
	v_mul_f32_e32 v93, 0x3fb8aa3b, v124
	v_mul_f32_e32 v90, 0x3fb8aa3b, v90
	v_exp_f32_e32 v92, v92
	v_mul_f32_e32 v91, 0x3fb8aa3b, v91
	v_exp_f32_e32 v93, v93
	v_exp_f32_e32 v90, v90
	v_exp_f32_e32 v91, v91
	v_lshlrev_b32_e32 v73, 16, v73
	v_pk_add_f32 v[92:93], v[92:93], 1.0 op_sel_hi:[1,0] neg_lo:[1,0] neg_hi:[1,0]
	v_mul_f32_e32 v73, v95, v73
	v_pk_mul_f32 v[90:91], v[92:93], v[90:91]
	v_add_f32_e32 v89, v89, v125
	v_cvt_pk_bf16_f32 v92, v90, s0
	ds_write_b16 v117, v92 offset:9248
	v_pk_mul_f32 v[92:93], v[90:91], v[78:79] op_sel_hi:[1,0]
	v_cvt_pk_bf16_f32 v90, v73, s0
	ds_write_b16 v117, v90 offset:816
	v_cvt_pk_bf16_f32 v90, v91, s0
	ds_write_b16 v117, v90 offset:9520
	v_sub_f32_e32 v90, v89, v77
	v_mul_f32_e32 v90, 0x3fb8aa3b, v90
	v_exp_f32_e32 v91, v90
	v_mul_f32_e32 v73, v94, v73
	v_cvt_pk_bf16_f32 v73, v73, s0
	ds_write_b16 v117, v73 offset:18224
	v_cvt_pk_bf16_f32 v73, v92, v93
	v_lshlrev_b32_e32 v92, 16, v88
	v_mul_f32_e32 v91, v91, v92
	v_cvt_pk_bf16_f32 v92, v91, s0
	ds_write_b16 v117, v92 offset:1088
	v_add_f32_e32 v92, v89, v126
	v_sub_f32_e32 v90, v77, v89
	v_sub_f32_e32 v89, v92, v77
	v_mul_f32_e32 v91, v94, v91
	v_mul_f32_e32 v89, 0x3fb8aa3b, v89
	v_cvt_pk_bf16_f32 v91, v91, s0
	v_exp_f32_e32 v93, v89
	v_sub_f32_e32 v89, v77, v92
	v_mul_f32_e32 v88, 0x3fb8aa3b, v125
	ds_write_b16 v117, v91 offset:18496
	v_mul_f32_e32 v91, 0x3fb8aa3b, v89
	v_mul_f32_e32 v89, 0x3fb8aa3b, v126
	v_mul_f32_e32 v90, 0x3fb8aa3b, v90
	v_exp_f32_e32 v88, v88
	v_exp_f32_e32 v89, v89
	v_exp_f32_e32 v90, v90
	v_exp_f32_e32 v91, v91
	v_lshlrev_b32_e32 v74, 16, v74
	v_pk_add_f32 v[88:89], v[88:89], 1.0 op_sel_hi:[1,0] neg_lo:[1,0] neg_hi:[1,0]
	v_mul_f32_e32 v74, v93, v74
	v_pk_mul_f32 v[88:89], v[88:89], v[90:91]
	v_lshlrev_b32_e32 v87, 16, v87
	v_cvt_pk_bf16_f32 v90, v88, s0
	ds_write_b16 v117, v90 offset:9792
	v_pk_mul_f32 v[90:91], v[88:89], v[78:79] op_sel_hi:[1,0]
	v_cvt_pk_bf16_f32 v88, v74, s0
	ds_write_b16 v117, v88 offset:1360
	v_cvt_pk_bf16_f32 v88, v89, s0
	v_add_f32_e32 v89, v92, v127
	ds_write_b16 v117, v88 offset:10064
	v_mul_f32_e32 v74, v94, v74
	v_sub_f32_e32 v88, v89, v77
	v_cvt_pk_bf16_f32 v74, v74, s0
	v_mul_f32_e32 v88, 0x3fb8aa3b, v88
	ds_write_b16 v117, v74 offset:18768
	v_cvt_pk_bf16_f32 v74, v90, v91
	v_exp_f32_e32 v91, v88
	v_sub_f32_e32 v88, v77, v89
	v_mul_f32_e32 v90, 0x3fb8aa3b, v127
	v_mul_f32_e32 v88, 0x3fb8aa3b, v88
	v_mul_f32_e32 v87, v91, v87
	v_cvt_pk_bf16_f32 v91, v87, s0
	v_mul_f32_e32 v87, v94, v87
	v_cvt_pk_bf16_f32 v87, v87, s0
	ds_write_b16 v117, v87 offset:19040
	v_add_f32_e32 v87, v89, v128
	v_sub_f32_e32 v89, v87, v77
	v_mul_f32_e32 v89, 0x3fb8aa3b, v89
	ds_write_b16 v117, v91 offset:1632
	v_exp_f32_e32 v92, v89
	v_sub_f32_e32 v89, v77, v87
	v_mul_f32_e32 v91, 0x3fb8aa3b, v128
	v_exp_f32_e32 v90, v90
	v_mul_f32_e32 v89, 0x3fb8aa3b, v89
	v_exp_f32_e32 v91, v91
	v_exp_f32_e32 v88, v88
	v_exp_f32_e32 v89, v89
	v_lshlrev_b32_e32 v75, 16, v75
	v_pk_add_f32 v[90:91], v[90:91], 1.0 op_sel_hi:[1,0] neg_lo:[1,0] neg_hi:[1,0]
	v_mul_f32_e32 v75, v92, v75
	v_pk_mul_f32 v[88:89], v[90:91], v[88:89]
	v_add_f32_e32 v87, v87, v129
	v_cvt_pk_bf16_f32 v90, v88, s0
	ds_write_b16 v117, v90 offset:10336
	v_pk_mul_f32 v[90:91], v[88:89], v[78:79] op_sel_hi:[1,0]
	v_cvt_pk_bf16_f32 v88, v75, s0
	ds_write_b16 v117, v88 offset:1904
	v_cvt_pk_bf16_f32 v88, v89, s0
	ds_write_b16 v117, v88 offset:10608
	v_sub_f32_e32 v88, v87, v77
	v_mul_f32_e32 v88, 0x3fb8aa3b, v88
	v_exp_f32_e32 v89, v88
	v_mul_f32_e32 v75, v94, v75
	v_cvt_pk_bf16_f32 v75, v75, s0
	ds_write_b16 v117, v75 offset:19312
	v_cvt_pk_bf16_f32 v75, v90, v91
	v_lshlrev_b32_e32 v90, 16, v86
	v_mul_f32_e32 v89, v89, v90
; DI u32 pack2bf(float lo, float hi) { f32x2 v = {lo, hi}; return __builtin_bit_cast(u32, __builtin_convertvector(v, bf2_t)); }
; DI u16 f2bf(float x) { return (u16)(pack2bf(x, 0.f) & 0xffffu); }
; DI float bf2f(u16 b) { return __uint_as_float(((u32)b) << 16); }
; template <int PASS>
; DI void hgrn_unit(const Params& p, int layer, int unit, char* smem) {
;     ...
;       for (int jj = 0; jj < 16; jj += 2) {
;         float kl2[2];
; #pragma unroll
;         for (int u = 0; u < 2; ++u) {
;           const int j = half * 16 + jj + u;
;           run += gval[jj + u];
;           float e1 = __expf(run - bmid), e2 = __expf(bmid - run);
;           float q = bf2f(qraw[jj + u]);
;           float k = 1.f - __expf(gval[jj + u]);
;           float qm = q * e1, km = k * e2;
;           kl2[u] = km * Elm;
;           sQm[j * HS + d] = f2bf(qm); sKm[j * HS + d] = f2bf(km); sQb[j * HS + d] = f2bf(qm * Emid);
;         }
;         klp[jj >> 1] = pack2bf(kl2[0], kl2[1]);
;       }
;     } else {
; #pragma unroll
;       for (int jj = 0; jj < 16; jj += 2) {
;         float kl2[2];
; #pragma unroll
;         for (int u = 0; u < 2; ++u) {
;           run += gval[jj + u];
;           kl2[u] = (1.f - __expf(gval[jj + u])) * __expf(blast - run);
;         }
;         klp[jj >> 1] = pack2bf(kl2[0], kl2[1]);
;       }
;     }
; #pragma unroll
;     for (int jj = 0; jj < 16; jj += 2)
;       vtp[jj >> 1] = (u32)vraw[jj] | ((u32)vraw[jj + 1] << 16);
;     {
;       u32x4 a = {klp[0], klp[1], klp[2], klp[3]}, b = {klp[4], klp[5], klp[6], klp[7]};
;       *(u32x4*)(sKlT + d * VS + half * 16) = a; *(u32x4*)(sKlT + d * VS + half * 16 + 8) = b;
;       u32x4 c0 = {vtp[0], vtp[1], vtp[2], vtp[3]}, c1 = {vtp[4], vtp[5], vtp[6], vtp[7]};
;       *(u32x4*)(sVt + d * VS + half * 16) = c0; *(u32x4*)(sVt + d * VS + half * 16 + 8) = c1;
;     }
;     if (half) sDec[d] = __expf(blast);
	v_cvt_pk_bf16_f32 v90, v89, s0
	ds_write_b16 v117, v90 offset:2176
	v_add_f32_e32 v90, v87, v130
	v_sub_f32_e32 v88, v77, v87
	v_sub_f32_e32 v87, v90, v77
	v_mul_f32_e32 v89, v94, v89
	v_mul_f32_e32 v87, 0x3fb8aa3b, v87
	v_cvt_pk_bf16_f32 v89, v89, s0
	v_exp_f32_e32 v91, v87
	v_sub_f32_e32 v87, v77, v90
	v_mul_f32_e32 v86, 0x3fb8aa3b, v129
	ds_write_b16 v117, v89 offset:19584
	v_mul_f32_e32 v89, 0x3fb8aa3b, v87
	v_mul_f32_e32 v87, 0x3fb8aa3b, v130
	v_mul_f32_e32 v88, 0x3fb8aa3b, v88
	v_exp_f32_e32 v86, v86
	v_exp_f32_e32 v87, v87
	v_exp_f32_e32 v88, v88
	v_exp_f32_e32 v89, v89
	v_lshlrev_b32_e32 v85, 16, v85
	v_pk_add_f32 v[86:87], v[86:87], 1.0 op_sel_hi:[1,0] neg_lo:[1,0] neg_hi:[1,0]
	v_mul_f32_e32 v85, v91, v85
	v_pk_mul_f32 v[86:87], v[86:87], v[88:89]
	v_lshlrev_b32_e32 v83, 16, v83
	v_cvt_pk_bf16_f32 v88, v86, s0
	ds_write_b16 v117, v88 offset:10880
	v_pk_mul_f32 v[88:89], v[86:87], v[78:79] op_sel_hi:[1,0]
	v_cvt_pk_bf16_f32 v86, v85, s0
	v_mul_f32_e32 v85, v94, v85
	v_cvt_pk_bf16_f32 v85, v85, s0
	ds_write_b16 v117, v85 offset:19856
	v_add_f32_e32 v85, v90, v131
	ds_write_b16 v117, v86 offset:2448
	v_cvt_pk_bf16_f32 v86, v87, s0
	v_sub_f32_e32 v87, v85, v77
	v_mul_f32_e32 v87, 0x3fb8aa3b, v87
	v_exp_f32_e32 v87, v87
	ds_write_b16 v117, v86 offset:11152
	v_cvt_pk_bf16_f32 v86, v88, v89
	v_lshlrev_b32_e32 v89, 16, v84
	v_mul_f32_e32 v87, v87, v89
	v_add_f32_e32 v90, v85, v132
	v_sub_f32_e32 v88, v77, v85
	v_cvt_pk_bf16_f32 v89, v87, s0
	v_mul_f32_e32 v87, v94, v87
	v_sub_f32_e32 v85, v90, v77
	v_cvt_pk_bf16_f32 v87, v87, s0
	v_mul_f32_e32 v85, 0x3fb8aa3b, v85
	ds_write_b16 v117, v87 offset:20128
	v_exp_f32_e32 v87, v85
	v_sub_f32_e32 v85, v77, v90
	v_mul_f32_e32 v84, 0x3fb8aa3b, v131
	ds_write_b16 v117, v89 offset:2720
	v_mul_f32_e32 v89, 0x3fb8aa3b, v85
	v_mul_f32_e32 v85, 0x3fb8aa3b, v132
	v_mul_f32_e32 v88, 0x3fb8aa3b, v88
	v_exp_f32_e32 v84, v84
	v_exp_f32_e32 v85, v85
	v_exp_f32_e32 v88, v88
	v_exp_f32_e32 v89, v89
	v_mul_f32_e32 v83, v87, v83
	v_pk_add_f32 v[84:85], v[84:85], 1.0 op_sel_hi:[1,0] neg_lo:[1,0] neg_hi:[1,0]
	v_lshlrev_b32_e32 v81, 16, v81
	v_pk_mul_f32 v[84:85], v[84:85], v[88:89]
	v_or_b32_sdwa v67, v67, v70 dst_sel:DWORD dst_unused:UNUSED_PAD src0_sel:DWORD src1_sel:WORD_0
	v_cvt_pk_bf16_f32 v87, v84, s0
	v_pk_mul_f32 v[88:89], v[84:85], v[78:79] op_sel_hi:[1,0]
	v_cvt_pk_bf16_f32 v84, v83, s0
	v_mul_f32_e32 v83, v94, v83
	v_cvt_pk_bf16_f32 v83, v83, s0
	ds_write_b16 v117, v84 offset:2992
	v_cvt_pk_bf16_f32 v84, v85, s0
	ds_write_b16 v117, v83 offset:20400
	v_add_f32_e32 v83, v90, v133
	ds_write_b16 v117, v84 offset:11696
	v_sub_f32_e32 v84, v83, v77
	v_mul_f32_e32 v84, 0x3fb8aa3b, v84
	v_exp_f32_e32 v85, v84
	ds_write_b16 v117, v87 offset:11424
	v_cvt_pk_bf16_f32 v87, v88, v89
	v_lshlrev_b32_e32 v88, 16, v82
	v_add_f32_e32 v89, v83, v136
	v_sub_f32_e32 v84, v77, v83
	v_mul_f32_e32 v85, v85, v88
	v_sub_f32_e32 v83, v89, v77
	v_cvt_pk_bf16_f32 v88, v85, s0
	v_mul_f32_e32 v85, v94, v85
	v_mul_f32_e32 v83, 0x3fb8aa3b, v83
	ds_write_b16 v117, v88 offset:3264
	v_cvt_pk_bf16_f32 v85, v85, s0
	v_exp_f32_e32 v88, v83
	v_sub_f32_e32 v83, v77, v89
	v_mul_f32_e32 v82, 0x3fb8aa3b, v133
	ds_write_b16 v117, v85 offset:20672
	v_mul_f32_e32 v85, 0x3fb8aa3b, v83
	v_mul_f32_e32 v83, 0x3fb8aa3b, v136
	v_mul_f32_e32 v84, 0x3fb8aa3b, v84
	v_exp_f32_e32 v82, v82
	v_exp_f32_e32 v83, v83
	v_exp_f32_e32 v84, v84
	v_exp_f32_e32 v85, v85
	v_mul_f32_e32 v81, v88, v81
	v_pk_add_f32 v[82:83], v[82:83], 1.0 op_sel_hi:[1,0] neg_lo:[1,0] neg_hi:[1,0]
	v_lshlrev_b32_e32 v70, 16, v142
	v_pk_mul_f32 v[82:83], v[82:83], v[84:85]
	v_lshlrev_b32_e32 v71, 16, v143
	v_cvt_pk_bf16_f32 v84, v82, s0
	ds_write_b16 v117, v84 offset:11968
	v_pk_mul_f32 v[84:85], v[82:83], v[78:79] op_sel_hi:[1,0]
	v_cvt_pk_bf16_f32 v82, v81, s0
	v_mul_f32_e32 v81, v94, v81
	v_cvt_pk_bf16_f32 v81, v81, s0
	ds_write_b16 v117, v82 offset:3536
	v_cvt_pk_bf16_f32 v82, v83, s0
	ds_write_b16 v117, v81 offset:20944
	v_add_f32_e32 v81, v89, v135
	ds_write_b16 v117, v82 offset:12240
	v_sub_f32_e32 v82, v81, v77
	v_mul_f32_e32 v82, 0x3fb8aa3b, v82
	v_exp_f32_e32 v83, v82
	v_cvt_pk_bf16_f32 v88, v84, v85
	v_lshlrev_b32_e32 v84, 16, v80
	v_sub_f32_e32 v82, v77, v81
	v_mul_f32_e32 v83, v83, v84
	v_cvt_pk_bf16_f32 v84, v83, s0
	v_mul_f32_e32 v83, v94, v83
	v_cvt_pk_bf16_f32 v83, v83, s0
	v_add_f32_e32 v81, v81, v134
	v_mul_f32_e32 v80, 0x3fb8aa3b, v135
	ds_write_b16 v117, v83 offset:21216
	v_sub_f32_e32 v83, v81, v77
	v_sub_f32_e32 v77, v77, v81
	v_mul_f32_e32 v81, 0x3fb8aa3b, v134
	v_mul_f32_e32 v82, 0x3fb8aa3b, v82
	v_exp_f32_e32 v80, v80
	v_mul_f32_e32 v83, 0x3fb8aa3b, v83
	v_mul_f32_e32 v77, 0x3fb8aa3b, v77
	v_exp_f32_e32 v81, v81
	v_exp_f32_e32 v82, v82
	ds_write_b16 v117, v84 offset:3808
	v_exp_f32_e32 v84, v83
	v_exp_f32_e32 v83, v77
	v_pk_add_f32 v[80:81], v[80:81], 1.0 op_sel_hi:[1,0] neg_lo:[1,0] neg_hi:[1,0]
	v_lshlrev_b32_e32 v77, 16, v79
	v_mul_f32_e32 v77, v84, v77
	v_pk_mul_f32 v[80:81], v[80:81], v[82:83]
	v_or_b32_sdwa v70, v70, v138 dst_sel:DWORD dst_unused:UNUSED_PAD src0_sel:DWORD src1_sel:WORD_0
	v_cvt_pk_bf16_f32 v79, v80, s0
	ds_write_b16 v117, v79 offset:12512
	v_pk_mul_f32 v[78:79], v[78:79], v[80:81] op_sel_hi:[0,1]
	v_cvt_pk_bf16_f32 v80, v77, s0
	v_mul_f32_e32 v77, v94, v77
	ds_write_b16 v117, v80 offset:4080
	v_cvt_pk_bf16_f32 v80, v81, s0
	v_cvt_pk_bf16_f32 v77, v77, s0
	v_or_b32_sdwa v71, v71, v139 dst_sel:DWORD dst_unused:UNUSED_PAD src0_sel:DWORD src1_sel:WORD_0
	ds_write_b16 v117, v80 offset:12784
	ds_write_b16 v117, v77 offset:21488
	v_cvt_pk_bf16_f32 v89, v78, v79
	ds_write_b128 v104, v[72:75] offset:26112
	ds_write_b128 v104, v[86:89] offset:26128
	ds_write_b128 v104, v[64:67] offset:36352
	ds_write_b128 v104, v[68:71] offset:36368
	s_and_saveexec_b64 s[74:75], s[4:5]
	s_cbranch_execz .LBB0_608
	v_mul_f32_e32 v64, 0x3fb8aa3b, v76
	v_exp_f32_e32 v64, v64
	ds_write_b32 v105, v64 offset:46592

; DI u32 pack2bf(float lo, float hi) { f32x2 v = {lo, hi}; return __builtin_bit_cast(u32, __builtin_convertvector(v, bf2_t)); }
; DI u16 f2bf(float x) { return (u16)(pack2bf(x, 0.f) & 0xffffu); }
; DI float bf2f(u16 b) { return __uint_as_float(((u32)b) << 16); }
; DI float h2f(u16 b) { return (float)__builtin_bit_cast(_Float16, b); }
; template <int PASS>
; DI void hgrn_unit(const Params& p, int layer, int unit, char* smem) {
;     ...
; #pragma unroll
;     for (int j = 0; j < 32; ++j) {
;       float g = h2f(rG[j * 64 + lane]);
;       if (j < 16) tot0 += g; else tot1 += g;
;       if (j == 16) g16 = g;
;       if ((j >> 4) == half) gval[j & 15] = g;
;     }
; #pragma unroll
;     for (int jj = 0; jj < 16; ++jj) { if (PASS == 2) qraw[jj] = rQ[jj * 64 + lane]; vraw[jj] = rV[jj * 64 + lane]; }
;     asm volatile("s_waitcnt lgkmcnt(0)" ::: "memory");
;     __builtin_amdgcn_sched_barrier(0);
;     if (c + 1 < c_end) gl(c + 1);
;     __syncthreads();
;     const float bmid = tot0 + g16, blast = tot0 + tot1;
;     logD += blast;
;     float run = half ? tot0 : 0.f;
;     u32 klp[8], vtp[8];
;     if (PASS == 2) {
;       const float Emid = __expf(bmid), Elm = __expf(blast - bmid);
; #pragma unroll
;       for (int jj = 0; jj < 16; jj += 2) {
;         float kl2[2];
; #pragma unroll
;         for (int u = 0; u < 2; ++u) {
;           const int j = half * 16 + jj + u;
;           run += gval[jj + u];
;           float e1 = __expf(run - bmid), e2 = __expf(bmid - run);
;           float q = bf2f(qraw[jj + u]);
;           float k = 1.f - __expf(gval[jj + u]);
;           float qm = q * e1, km = k * e2;
;           kl2[u] = km * Elm;
;           sQm[j * HS + d] = f2bf(qm); sKm[j * HS + d] = f2bf(km); sQb[j * HS + d] = f2bf(qm * Emid);
;         }
;         klp[jj >> 1] = pack2bf(kl2[0], kl2[1]);
;       }
;     } else {
; #pragma unroll
;       for (int jj = 0; jj < 16; jj += 2) {
;         float kl2[2];
; #pragma unroll
;         for (int u = 0; u < 2; ++u) {
;           run += gval[jj + u];
;           kl2[u] = (1.f - __expf(gval[jj + u])) * __expf(blast - run);
;         }
;         klp[jj >> 1] = pack2bf(kl2[0], kl2[1]);
;       }
;     }
; #pragma unroll
;     for (int jj = 0; jj < 16; jj += 2)
;       vtp[jj >> 1] = (u32)vraw[jj] | ((u32)vraw[jj + 1] << 16);
.LBB0_1322:
	s_waitcnt lgkmcnt(0)
	v_cvt_f32_f16_e32 v152, v152
	v_cvt_f32_f16_e32 v151, v151
	v_cvt_f32_f16_e32 v150, v150
	v_cvt_f32_f16_e32 v149, v149
	v_add_f32_e32 v153, 0, v152
	v_cvt_f32_f16_e32 v148, v148
	v_cndmask_b32_e32 v111, v111, v152, vcc
	v_add_f32_e32 v152, v153, v151
	v_cvt_f32_f16_e32 v147, v147
	v_cndmask_b32_e32 v110, v110, v151, vcc
	v_add_f32_e32 v151, v152, v150
	v_cvt_f32_f16_e32 v146, v146
	v_cndmask_b32_e32 v109, v109, v150, vcc
	v_add_f32_e32 v150, v151, v149
	v_cvt_f32_f16_e32 v145, v145
	v_cndmask_b32_e32 v108, v108, v149, vcc
	v_add_f32_e32 v149, v150, v148
	v_cvt_f32_f16_e32 v144, v144
	v_cndmask_b32_e32 v107, v107, v148, vcc
	v_add_f32_e32 v148, v149, v147
	v_cvt_f32_f16_e32 v143, v143
	v_cndmask_b32_e32 v106, v106, v147, vcc
	v_add_f32_e32 v147, v148, v146
	v_cvt_f32_f16_e32 v142, v142
	v_cndmask_b32_e32 v105, v105, v146, vcc
	v_add_f32_e32 v146, v147, v145
	v_cvt_f32_f16_e32 v141, v141
	v_cndmask_b32_e32 v104, v104, v145, vcc
	v_add_f32_e32 v145, v146, v144
	v_cvt_f32_f16_e32 v140, v140
	v_cndmask_b32_e32 v103, v103, v144, vcc
	v_add_f32_e32 v144, v145, v143
	v_cvt_f32_f16_e32 v139, v139
	v_cndmask_b32_e32 v102, v102, v143, vcc
	v_add_f32_e32 v143, v144, v142
	v_cvt_f32_f16_e32 v138, v138
	v_cndmask_b32_e32 v101, v101, v142, vcc
	v_add_f32_e32 v142, v143, v141
	v_cndmask_b32_e32 v100, v100, v141, vcc
	v_add_f32_e32 v141, v142, v140
	v_cndmask_b32_e32 v99, v99, v140, vcc
	v_add_f32_e32 v140, v141, v139
	v_cndmask_b32_e32 v98, v98, v139, vcc
	v_cvt_f32_f16_e32 v137, v137
	v_add_f32_e32 v139, v140, v138
	v_cndmask_b32_e32 v94, v94, v138, vcc
	v_cvt_f32_f16_e32 v138, v64
	v_cvt_f32_f16_e32 v136, v136
	v_cvt_f32_f16_e32 v135, v135
	v_cvt_f32_f16_e32 v134, v134
	v_add_f32_e32 v64, v139, v137
	v_cndmask_b32_e32 v75, v75, v137, vcc
	v_add_f32_e32 v137, 0, v138
	v_cvt_f32_f16_e32 v133, v133
	v_add_f32_e32 v137, v137, v136
	v_cvt_f32_f16_e32 v132, v132
	v_cndmask_b32_e64 v110, v110, v136, s[6:7]
	v_add_f32_e32 v136, v137, v135
	v_cvt_f32_f16_e32 v131, v131
	v_cndmask_b32_e64 v109, v109, v135, s[6:7]
	v_add_f32_e32 v135, v136, v134
	v_cvt_f32_f16_e32 v130, v130
	v_cndmask_b32_e64 v108, v108, v134, s[6:7]
	v_add_f32_e32 v134, v135, v133
	v_cvt_f32_f16_e32 v129, v129
	v_cndmask_b32_e64 v107, v107, v133, s[6:7]
	v_add_f32_e32 v133, v134, v132
	v_cvt_f32_f16_e32 v128, v128
	v_cndmask_b32_e64 v106, v106, v132, s[6:7]
	v_add_f32_e32 v132, v133, v131
	v_cvt_f32_f16_e32 v127, v127
	v_cndmask_b32_e64 v105, v105, v131, s[6:7]
	v_add_f32_e32 v131, v132, v130
	v_cvt_f32_f16_e32 v126, v126
	v_cndmask_b32_e64 v104, v104, v130, s[6:7]
	v_add_f32_e32 v130, v131, v129
	v_cvt_f32_f16_e32 v125, v125
	v_cndmask_b32_e64 v103, v103, v129, s[6:7]
	v_add_f32_e32 v129, v130, v128
	v_cvt_f32_f16_e32 v124, v124
	v_cndmask_b32_e64 v102, v102, v128, s[6:7]
	v_add_f32_e32 v128, v129, v127
	v_cndmask_b32_e64 v101, v101, v127, s[6:7]
	v_add_f32_e32 v127, v128, v126
	v_cndmask_b32_e64 v100, v100, v126, s[6:7]
	v_add_f32_e32 v126, v127, v125
	v_cvt_f32_f16_e32 v123, v123
	v_cndmask_b32_e64 v99, v99, v125, s[6:7]
	v_add_f32_e32 v125, v126, v124
	v_cvt_f32_f16_e32 v126, v74
	v_lshlrev_b32_e32 v115, 16, v115
	v_cndmask_b32_e64 v98, v98, v124, s[6:7]
	v_or_b32_sdwa v124, v115, v65 dst_sel:DWORD dst_unused:UNUSED_PAD src0_sel:DWORD src1_sel:WORD_0
	v_lshlrev_b32_e32 v65, 16, v116
	v_add_f32_e32 v74, v125, v123
	v_or_b32_sdwa v125, v65, v66 dst_sel:DWORD dst_unused:UNUSED_PAD src0_sel:DWORD src1_sel:WORD_0
	v_lshlrev_b32_e32 v65, 16, v117
	v_add_f32_e32 v74, v74, v126
	v_cndmask_b32_e64 v75, v75, v126, s[6:7]
	v_or_b32_sdwa v126, v65, v67 dst_sel:DWORD dst_unused:UNUSED_PAD src0_sel:DWORD src1_sel:WORD_0
	v_lshlrev_b32_e32 v65, 16, v118
	v_or_b32_sdwa v127, v65, v80 dst_sel:DWORD dst_unused:UNUSED_PAD src0_sel:DWORD src1_sel:WORD_0
	v_lshlrev_b32_e32 v65, 16, v119
	v_or_b32_sdwa v116, v65, v81 dst_sel:DWORD dst_unused:UNUSED_PAD src0_sel:DWORD src1_sel:WORD_0
	v_lshlrev_b32_e32 v65, 16, v120
	v_or_b32_sdwa v117, v65, v112 dst_sel:DWORD dst_unused:UNUSED_PAD src0_sel:DWORD src1_sel:WORD_0
	v_lshlrev_b32_e32 v65, 16, v121
	v_cndmask_b32_e64 v111, v111, v138, s[6:7]
	v_or_b32_sdwa v118, v65, v113 dst_sel:DWORD dst_unused:UNUSED_PAD src0_sel:DWORD src1_sel:WORD_0
	v_lshlrev_b32_e32 v65, 16, v122
	v_or_b32_sdwa v119, v65, v114 dst_sel:DWORD dst_unused:UNUSED_PAD src0_sel:DWORD src1_sel:WORD_0
	v_mul_f32_e32 v65, 0x3fb8aa3b, v111
	v_exp_f32_e32 v66, v65
	v_mul_f32_e32 v65, 0x3fb8aa3b, v110
	v_exp_f32_e32 v67, v65
	v_cndmask_b32_e64 v65, v64, 0, vcc
	v_add_f32_e32 v134, v65, v111
; DI u32 pack2bf(float lo, float hi) { f32x2 v = {lo, hi}; return __builtin_bit_cast(u32, __builtin_convertvector(v, bf2_t)); }
; template <int PASS>
; DI void hgrn_unit(const Params& p, int layer, int unit, char* smem) {
;     ...
;       for (int jj = 0; jj < 16; jj += 2) {
;         float kl2[2];
; #pragma unroll
;         for (int u = 0; u < 2; ++u) {
;           run += gval[jj + u];
;           kl2[u] = (1.f - __expf(gval[jj + u])) * __expf(blast - run);
;         }
;         klp[jj >> 1] = pack2bf(kl2[0], kl2[1]);
;       }
;     }
; #pragma unroll
;     for (int jj = 0; jj < 16; jj += 2)
;       vtp[jj >> 1] = (u32)vraw[jj] | ((u32)vraw[jj + 1] << 16);
;     {
;       u32x4 a = {klp[0], klp[1], klp[2], klp[3]}, b = {klp[4], klp[5], klp[6], klp[7]};
;       *(u32x4*)(sKlT + d * VS + half * 16) = a; *(u32x4*)(sKlT + d * VS + half * 16 + 8) = b;
;       u32x4 c0 = {vtp[0], vtp[1], vtp[2], vtp[3]}, c1 = {vtp[4], vtp[5], vtp[6], vtp[7]};
;       *(u32x4*)(sVt + d * VS + half * 16) = c0; *(u32x4*)(sVt + d * VS + half * 16 + 8) = c1;
;     }
;     if (half) sDec[d] = __expf(blast);
;     __syncthreads();
	v_mul_f32_e32 v65, 0x3fb8aa3b, v109
	v_exp_f32_e32 v80, v65
	v_mul_f32_e32 v65, 0x3fb8aa3b, v108
	v_add_f32_e32 v135, v134, v110
	v_exp_f32_e32 v81, v65
	v_add_f32_e32 v136, v135, v109
	v_mul_f32_e32 v65, 0x3fb8aa3b, v107
	v_add_f32_e32 v137, v136, v108
	v_exp_f32_e32 v112, v65
	v_mul_f32_e32 v65, 0x3fb8aa3b, v106
	v_exp_f32_e32 v113, v65
	v_add_f32_e32 v138, v137, v107
	v_mul_f32_e32 v65, 0x3fb8aa3b, v105
	v_pk_add_f32 v[114:115], v[80:81], 1.0 op_sel_hi:[1,0] neg_lo:[1,0] neg_hi:[1,0]
	v_add_f32_e32 v139, v138, v106
	v_exp_f32_e32 v80, v65
	v_mul_f32_e32 v65, 0x3fb8aa3b, v104
	v_add_f32_e32 v140, v139, v105
	v_exp_f32_e32 v81, v65
	v_add_f32_e32 v141, v140, v104
	v_mul_f32_e32 v65, 0x3fb8aa3b, v103
	v_pk_add_f32 v[120:121], v[112:113], 1.0 op_sel_hi:[1,0] neg_lo:[1,0] neg_hi:[1,0]
	v_exp_f32_e32 v112, v65
	v_mul_f32_e32 v65, 0x3fb8aa3b, v102
	v_add_f32_e32 v142, v141, v103
	v_exp_f32_e32 v113, v65
	v_add_f32_e32 v143, v142, v102
	v_mul_f32_e32 v65, 0x3fb8aa3b, v101
	v_cndmask_b32_e64 v94, v94, v123, s[6:7]
	v_pk_add_f32 v[122:123], v[80:81], 1.0 op_sel_hi:[1,0] neg_lo:[1,0] neg_hi:[1,0]
	v_add_f32_e32 v144, v143, v101
	v_exp_f32_e32 v80, v65
	v_mul_f32_e32 v65, 0x3fb8aa3b, v100
	v_add_f32_e32 v145, v144, v100
	v_exp_f32_e32 v81, v65
	v_mul_f32_e32 v65, 0x3fb8aa3b, v99
	v_add_f32_e32 v146, v145, v99
	v_pk_add_f32 v[128:129], v[112:113], 1.0 op_sel_hi:[1,0] neg_lo:[1,0] neg_hi:[1,0]
	v_exp_f32_e32 v112, v65
	v_mul_f32_e32 v65, 0x3fb8aa3b, v98
	v_add_f32_e32 v147, v146, v98
	v_exp_f32_e32 v113, v65
	v_add_f32_e32 v65, v147, v94
	v_pk_add_f32 v[130:131], v[80:81], 1.0 op_sel_hi:[1,0] neg_lo:[1,0] neg_hi:[1,0]
	v_pk_add_f32 v[80:81], v[64:65], v[74:75]
	v_pk_add_f32 v[132:133], v[112:113], 1.0 op_sel_hi:[1,0] neg_lo:[1,0] neg_hi:[1,0]
	v_sub_f32_e32 v64, v80, v134
	v_mul_f32_e32 v64, 0x3fb8aa3b, v64
	v_exp_f32_e32 v112, v64
	v_sub_f32_e32 v64, v80, v135
	v_mul_f32_e32 v64, 0x3fb8aa3b, v64
	v_exp_f32_e32 v113, v64
	v_sub_f32_e32 v64, v80, v136
	v_mul_f32_e32 v64, 0x3fb8aa3b, v64
	v_exp_f32_e32 v134, v64
	v_sub_f32_e32 v64, v80, v137
	v_mul_f32_e32 v64, 0x3fb8aa3b, v64
	v_exp_f32_e32 v135, v64
	v_pk_add_f32 v[66:67], v[66:67], 1.0 op_sel_hi:[1,0] neg_lo:[1,0] neg_hi:[1,0]
	v_sub_f32_e32 v74, v80, v138
	v_pk_mul_f32 v[66:67], v[66:67], v[112:113]
	v_mul_f32_e32 v74, 0x3fb8aa3b, v74
	v_cvt_pk_bf16_f32 v112, v66, v67
	v_pk_mul_f32 v[66:67], v[114:115], v[134:135]
	v_exp_f32_e32 v114, v74
	v_sub_f32_e32 v74, v80, v139
	v_mul_f32_e32 v74, 0x3fb8aa3b, v74
	v_exp_f32_e32 v115, v74
	v_sub_f32_e32 v74, v80, v140
	v_mul_f32_e32 v74, 0x3fb8aa3b, v74
	v_exp_f32_e32 v134, v74
	v_sub_f32_e32 v74, v80, v141
	v_mul_f32_e32 v74, 0x3fb8aa3b, v74
	v_exp_f32_e32 v135, v74
	v_sub_f32_e32 v74, v80, v142
	v_mul_f32_e32 v74, 0x3fb8aa3b, v74
	v_cvt_pk_bf16_f32 v113, v66, v67
	v_pk_mul_f32 v[66:67], v[120:121], v[114:115]
	v_exp_f32_e32 v120, v74
	v_sub_f32_e32 v74, v80, v143
	v_mul_f32_e32 v74, 0x3fb8aa3b, v74
	v_exp_f32_e32 v121, v74
	v_sub_f32_e32 v74, v80, v144
	v_mul_f32_e32 v74, 0x3fb8aa3b, v74
	v_cvt_pk_bf16_f32 v114, v66, v67
	v_pk_mul_f32 v[66:67], v[122:123], v[134:135]
	v_exp_f32_e32 v122, v74
	v_sub_f32_e32 v74, v80, v145
	v_mul_f32_e32 v74, 0x3fb8aa3b, v74
	v_exp_f32_e32 v123, v74
	v_cvt_pk_bf16_f32 v115, v66, v67
	v_pk_mul_f32 v[66:67], v[128:129], v[120:121]
	v_sub_f32_e32 v65, v80, v65
	v_cvt_pk_bf16_f32 v120, v66, v67
	v_pk_mul_f32 v[66:67], v[130:131], v[122:123]
	v_mul_f32_e32 v65, 0x3fb8aa3b, v65
	v_mul_f32_e32 v148, 0x3fb8aa3b, v94
	v_cvt_pk_bf16_f32 v121, v66, v67
	v_sub_f32_e32 v66, v80, v146
	v_sub_f32_e32 v67, v80, v147
	v_exp_f32_e32 v128, v65
	v_mul_f32_e32 v65, 0x3fb8aa3b, v75
	v_sub_f32_e32 v74, v80, v81
	v_exp_f32_e32 v64, v148
	v_mul_f32_e32 v66, 0x3fb8aa3b, v66
	v_mul_f32_e32 v67, 0x3fb8aa3b, v67
	v_exp_f32_e32 v65, v65
	v_mul_f32_e32 v74, 0x3fb8aa3b, v74
	v_exp_f32_e32 v66, v66
	v_exp_f32_e32 v67, v67
	v_exp_f32_e32 v129, v74
	v_pk_add_f32 v[64:65], v[64:65], 1.0 op_sel_hi:[1,0] neg_lo:[1,0] neg_hi:[1,0]
	s_nop 0
	v_pk_mul_f32 v[66:67], v[132:133], v[66:67]
	v_pk_mul_f32 v[64:65], v[64:65], v[128:129]
	s_barrier
	v_cvt_pk_bf16_f32 v122, v66, v67
	v_cvt_pk_bf16_f32 v123, v64, v65
	ds_write_b128 v83, v[112:115] offset:26112
	ds_write_b128 v83, v[120:123] offset:26128
	ds_write_b128 v83, v[124:127] offset:36352
	ds_write_b128 v83, v[116:119] offset:36368
	s_and_saveexec_b64 s[12:13], s[0:1]
	s_cbranch_execz .LBB0_1319
	v_mul_f32_e32 v64, 0x3fb8aa3b, v80
	v_exp_f32_e32 v64, v64
	ds_write_b32 v82, v64 offset:46592
	s_branch .LBB0_1319
